# P10 down-GEMM epilogue rewritten by hand: per row both 128B lines of the f32 residual read-modify-written together, 3-deep rolling load pipeline
# speedup vs baseline: 1.0152x; 1.0152x over previous
;     __device__ __forceinline__ void operator()(const f32x4 (&acc)[2][2][4][2], const Unit& u, int wr, int wc, int fr, int fq) const {
;         const int row0 = u.pm * 256 + wr * 64 + fr; const int col0 = u.pn * 256 + wc * 32 + 4 * fq;
;         const float* gp = gate + (size_t)(u.pm / 16) * ADAW;
; #pragma unroll
;         for (int bj = 0; bj < 2; ++bj)
; #pragma unroll
;             for (int n = 0; n < 2; ++n) {
;                 const int col = col0 + bj * HALF + n * 16;
;                 const f32x4 g = *(const f32x4*)(gp + col);
; #pragma unroll
;                 for (int ai = 0; ai < 2; ++ai)
; #pragma unroll
;                     for (int m = 0; m < 4; ++m) {
;                         const size_t off = (size_t)(row0 + ai * HALF + m * 16) * D + col;
;                         *(f32x4*)(out + off) = *(const f32x4*)(base + off) + g * acc[ai][bj][m][n];
;                     }
;             }
;     }
.LBB0_914:
	v_lshl_add_u32 v210, s49, 8, v218
	v_lshl_add_u32 v212, s50, 8, v220
	v_mov_b32_e32 v211, 0
	v_mov_b32_e32 v213, 0
	v_lshlrev_b64 v[210:211], 12, v[210:211]
	v_lshlrev_b32_e32 v212, 2, v212
	s_lshr_b32 s18, s49, 4
	s_mul_i32 s18, s18, 0x6000
	s_add_u32 s18, s28, s18
	s_addc_u32 s19, s29, 0
	v_lshl_add_u64 v[192:193], s[26:27], 0, v[210:211]
	v_lshl_add_u64 v[208:209], s[18:19], 0, v[212:213]
	v_lshl_add_u64 v[192:193], v[192:193], 0, v[212:213]
	global_load_dwordx4 v[224:227], v[208:209], off
	global_load_dwordx4 v[228:231], v[208:209], off offset:64
	global_load_dwordx4 v[232:235], v[208:209], off offset:512
	global_load_dwordx4 v[236:239], v[208:209], off offset:576
	global_load_dwordx4 v[128:131], v[192:193], off
	global_load_dwordx4 v[132:135], v[192:193], off offset:64
	global_load_dwordx4 v[136:139], v[192:193], off offset:512
	global_load_dwordx4 v[140:143], v[192:193], off offset:576
	s_mov_b64 s[18:19], 0x10000
	v_lshl_add_u64 v[194:195], v[192:193], 0, s[18:19]
	global_load_dwordx4 v[144:147], v[194:195], off
	global_load_dwordx4 v[148:151], v[194:195], off offset:64
	global_load_dwordx4 v[152:155], v[194:195], off offset:512
	global_load_dwordx4 v[156:159], v[194:195], off offset:576
	s_mov_b64 s[18:19], 0x20000
	v_lshl_add_u64 v[196:197], v[192:193], 0, s[18:19]
	global_load_dwordx4 v[160:163], v[196:197], off
	global_load_dwordx4 v[164:167], v[196:197], off offset:64
	global_load_dwordx4 v[168:171], v[196:197], off offset:512
	global_load_dwordx4 v[172:175], v[196:197], off offset:576
	s_mov_b64 s[18:19], 0x30000
	v_lshl_add_u64 v[198:199], v[192:193], 0, s[18:19]
	v_lshl_add_u64 v[200:201], v[192:193], 0, s[10:11]
	v_lshl_add_u64 v[202:203], v[192:193], 0, s[12:13]
	v_lshl_add_u64 v[204:205], v[192:193], 0, s[14:15]
	v_lshl_add_u64 v[206:207], v[192:193], 0, s[6:7]
	s_waitcnt vmcnt(8)
	v_pk_fma_f32 v[124:125], v[124:125], v[224:225], v[128:129]
	v_pk_fma_f32 v[126:127], v[126:127], v[226:227], v[130:131]
	v_pk_fma_f32 v[108:109], v[108:109], v[228:229], v[132:133]
	v_pk_fma_f32 v[110:111], v[110:111], v[230:231], v[134:135]
	v_pk_fma_f32 v[80:81], v[80:81], v[232:233], v[136:137]
	v_pk_fma_f32 v[82:83], v[82:83], v[234:235], v[138:139]
	v_pk_fma_f32 v[48:49], v[48:49], v[236:237], v[140:141]
	v_pk_fma_f32 v[50:51], v[50:51], v[238:239], v[142:143]
	global_store_dwordx4 v[192:193], v[124:127], off
	global_store_dwordx4 v[192:193], v[108:111], off offset:64
	global_store_dwordx4 v[192:193], v[80:83], off offset:512
	global_store_dwordx4 v[192:193], v[48:51], off offset:576
	global_load_dwordx4 v[128:131], v[198:199], off
	global_load_dwordx4 v[132:135], v[198:199], off offset:64
	global_load_dwordx4 v[136:139], v[198:199], off offset:512
	global_load_dwordx4 v[140:143], v[198:199], off offset:576
	s_waitcnt vmcnt(12)
	v_pk_fma_f32 v[120:121], v[120:121], v[224:225], v[144:145]
	v_pk_fma_f32 v[122:123], v[122:123], v[226:227], v[146:147]
	v_pk_fma_f32 v[104:105], v[104:105], v[228:229], v[148:149]
	v_pk_fma_f32 v[106:107], v[106:107], v[230:231], v[150:151]
	v_pk_fma_f32 v[76:77], v[76:77], v[232:233], v[152:153]
	v_pk_fma_f32 v[78:79], v[78:79], v[234:235], v[154:155]
	v_pk_fma_f32 v[40:41], v[40:41], v[236:237], v[156:157]
	v_pk_fma_f32 v[42:43], v[42:43], v[238:239], v[158:159]
	global_store_dwordx4 v[194:195], v[120:123], off
	global_store_dwordx4 v[194:195], v[104:107], off offset:64
	global_store_dwordx4 v[194:195], v[76:79], off offset:512
	global_store_dwordx4 v[194:195], v[40:43], off offset:576
	global_load_dwordx4 v[144:147], v[200:201], off
	global_load_dwordx4 v[148:151], v[200:201], off offset:64
	global_load_dwordx4 v[152:155], v[200:201], off offset:512
	global_load_dwordx4 v[156:159], v[200:201], off offset:576
	s_waitcnt vmcnt(16)
	v_pk_fma_f32 v[116:117], v[116:117], v[224:225], v[160:161]
	v_pk_fma_f32 v[118:119], v[118:119], v[226:227], v[162:163]
	v_pk_fma_f32 v[100:101], v[100:101], v[228:229], v[164:165]
	v_pk_fma_f32 v[102:103], v[102:103], v[230:231], v[166:167]
	v_pk_fma_f32 v[64:65], v[64:65], v[232:233], v[168:169]
	v_pk_fma_f32 v[66:67], v[66:67], v[234:235], v[170:171]
	v_pk_fma_f32 v[36:37], v[36:37], v[236:237], v[172:173]
	v_pk_fma_f32 v[38:39], v[38:39], v[238:239], v[174:175]
	global_store_dwordx4 v[196:197], v[116:119], off
	global_store_dwordx4 v[196:197], v[100:103], off offset:64
	global_store_dwordx4 v[196:197], v[64:67], off offset:512
	global_store_dwordx4 v[196:197], v[36:39], off offset:576
	global_load_dwordx4 v[160:163], v[202:203], off
	global_load_dwordx4 v[164:167], v[202:203], off offset:64
	global_load_dwordx4 v[168:171], v[202:203], off offset:512
	global_load_dwordx4 v[172:175], v[202:203], off offset:576
	s_waitcnt vmcnt(16)
; #define PG8_BAR __builtin_amdgcn_s_barrier()
; template <class Epi, class Sched, bool ALIGN_EPI = false, bool SP2 = false>
; __device__ __forceinline__ void gemm_phase(PG8_LAS unsigned char* lds, const Gemm g, const Sched& S, const Epi& E, int wave_in) {
;     ...
;         if (!has_next) break;
; #pragma unroll
;         for (int a = 0; a < 2; ++a)
; #pragma unroll
;             for (int b = 0; b < 2; ++b)
; #pragma unroll
;                 for (int m = 0; m < 4; ++m)
; #pragma unroll
;                     for (int n = 0; n < 2; ++n) acc[a][b][m][n] = (f32x4){0.f, 0.f, 0.f, 0.f};
;         cur = nxt; cA = nA; cB = nB; ++ui;
;         if constexpr (ALIGN_EPI) { if (wr == 1) PG8_BAR; }
;     __device__ __forceinline__ void operator()(const f32x4 (&acc)[2][2][4][2], const Unit& u, int wr, int wc, int fr, int fq) const {
;     ...
;                 const f32x4 g = *(const f32x4*)(gp + col);
; #pragma unroll
;                 for (int ai = 0; ai < 2; ++ai)
; #pragma unroll
;                     for (int m = 0; m < 4; ++m) {
;                         const size_t off = (size_t)(row0 + ai * HALF + m * 16) * D + col;
;                         *(f32x4*)(out + off) = *(const f32x4*)(base + off) + g * acc[ai][bj][m][n];
;                     }
;             }
	v_pk_fma_f32 v[112:113], v[112:113], v[224:225], v[128:129]
	v_pk_fma_f32 v[114:115], v[114:115], v[226:227], v[130:131]
	v_pk_fma_f32 v[96:97], v[96:97], v[228:229], v[132:133]
	v_pk_fma_f32 v[98:99], v[98:99], v[230:231], v[134:135]
	v_pk_fma_f32 v[56:57], v[56:57], v[232:233], v[136:137]
	v_pk_fma_f32 v[58:59], v[58:59], v[234:235], v[138:139]
	v_pk_fma_f32 v[32:33], v[32:33], v[236:237], v[140:141]
	v_pk_fma_f32 v[34:35], v[34:35], v[238:239], v[142:143]
	global_store_dwordx4 v[198:199], v[112:115], off
	global_store_dwordx4 v[198:199], v[96:99], off offset:64
	global_store_dwordx4 v[198:199], v[56:59], off offset:512
	global_store_dwordx4 v[198:199], v[32:35], off offset:576
	global_load_dwordx4 v[128:131], v[204:205], off
	global_load_dwordx4 v[132:135], v[204:205], off offset:64
	global_load_dwordx4 v[136:139], v[204:205], off offset:512
	global_load_dwordx4 v[140:143], v[204:205], off offset:576
	s_waitcnt vmcnt(16)
	v_pk_fma_f32 v[92:93], v[92:93], v[224:225], v[144:145]
	v_pk_fma_f32 v[94:95], v[94:95], v[226:227], v[146:147]
	v_pk_fma_f32 v[68:69], v[68:69], v[228:229], v[148:149]
	v_pk_fma_f32 v[70:71], v[70:71], v[230:231], v[150:151]
	v_pk_fma_f32 v[28:29], v[28:29], v[232:233], v[152:153]
	v_pk_fma_f32 v[30:31], v[30:31], v[234:235], v[154:155]
	v_pk_fma_f32 v[12:13], v[12:13], v[236:237], v[156:157]
	v_pk_fma_f32 v[14:15], v[14:15], v[238:239], v[158:159]
	global_store_dwordx4 v[200:201], v[92:95], off
	global_store_dwordx4 v[200:201], v[68:71], off offset:64
	global_store_dwordx4 v[200:201], v[28:31], off offset:512
	global_store_dwordx4 v[200:201], v[12:15], off offset:576
	global_load_dwordx4 v[144:147], v[206:207], off
	global_load_dwordx4 v[148:151], v[206:207], off offset:64
	global_load_dwordx4 v[152:155], v[206:207], off offset:512
	global_load_dwordx4 v[156:159], v[206:207], off offset:576
	s_waitcnt vmcnt(16)
	v_pk_fma_f32 v[88:89], v[88:89], v[224:225], v[160:161]
	v_pk_fma_f32 v[90:91], v[90:91], v[226:227], v[162:163]
	v_pk_fma_f32 v[60:61], v[60:61], v[228:229], v[164:165]
	v_pk_fma_f32 v[62:63], v[62:63], v[230:231], v[166:167]
	v_pk_fma_f32 v[24:25], v[24:25], v[232:233], v[168:169]
	v_pk_fma_f32 v[26:27], v[26:27], v[234:235], v[170:171]
	v_pk_fma_f32 v[8:9], v[8:9], v[236:237], v[172:173]
	v_pk_fma_f32 v[10:11], v[10:11], v[238:239], v[174:175]
	global_store_dwordx4 v[202:203], v[88:91], off
	global_store_dwordx4 v[202:203], v[60:63], off offset:64
	global_store_dwordx4 v[202:203], v[24:27], off offset:512
	global_store_dwordx4 v[202:203], v[8:11], off offset:576
	s_waitcnt vmcnt(12)
	v_pk_fma_f32 v[84:85], v[84:85], v[224:225], v[128:129]
	v_pk_fma_f32 v[86:87], v[86:87], v[226:227], v[130:131]
	v_pk_fma_f32 v[52:53], v[52:53], v[228:229], v[132:133]
	v_pk_fma_f32 v[54:55], v[54:55], v[230:231], v[134:135]
	v_pk_fma_f32 v[20:21], v[20:21], v[232:233], v[136:137]
	v_pk_fma_f32 v[22:23], v[22:23], v[234:235], v[138:139]
	v_pk_fma_f32 v[4:5], v[4:5], v[236:237], v[140:141]
	v_pk_fma_f32 v[6:7], v[6:7], v[238:239], v[142:143]
	global_store_dwordx4 v[204:205], v[84:87], off
	global_store_dwordx4 v[204:205], v[52:55], off offset:64
	global_store_dwordx4 v[204:205], v[20:23], off offset:512
	global_store_dwordx4 v[204:205], v[4:7], off offset:576
	s_waitcnt vmcnt(8)
	v_pk_fma_f32 v[72:73], v[72:73], v[224:225], v[144:145]
	v_pk_fma_f32 v[74:75], v[74:75], v[226:227], v[146:147]
	v_pk_fma_f32 v[44:45], v[44:45], v[228:229], v[148:149]
	v_pk_fma_f32 v[46:47], v[46:47], v[230:231], v[150:151]
	v_pk_fma_f32 v[16:17], v[16:17], v[232:233], v[152:153]
	v_pk_fma_f32 v[18:19], v[18:19], v[234:235], v[154:155]
	v_pk_fma_f32 v[0:1], v[0:1], v[236:237], v[156:157]
	v_pk_fma_f32 v[2:3], v[2:3], v[238:239], v[158:159]
	global_store_dwordx4 v[206:207], v[72:75], off
	global_store_dwordx4 v[206:207], v[44:47], off offset:64
	global_store_dwordx4 v[206:207], v[16:19], off offset:512
	global_store_dwordx4 v[206:207], v[0:3], off offset:576
	s_and_b64 vcc, exec, s[0:1]
	s_mov_b64 s[0:1], -1
	s_cbranch_vccnz .LBB0_899
	s_and_b64 vcc, exec, s[62:63]
	s_cbranch_vccnz .LBB0_898
	s_barrier
	s_branch .LBB0_898
